# v15: like v10 but 4608 (instead of 3072) layer-1 conversion items moved to idle CUs of layer-0 FFN2 last round
# speedup vs baseline: 1.0461x; 1.0054x over previous
; __device__ __forceinline__ void phase_prologue(PtrTab TB, unsigned char* ws, float* xout, int l, LAS unsigned char* lds, int gw, int NGW, int lane, int wave) {
;     ...
;     for (int it = gw; it < S14; it += NGW) {
.LBB0_23:
	s_cmpk_eq_u32 s8, 0x800
	s_cbranch_scc0 .Ltr_start
	s_cmpk_eq_u32 s94, 1
	s_cbranch_scc0 .Ltr_start
	s_cmpk_lt_u32 s71, 0x1200
	s_cbranch_scc0 .Ltr_start
	s_addk_i32 s71, 0x1200

; #define LAS __attribute__((address_space(3)))
; __device__ __forceinline__ void tr_item(const float* W, int ldn, int col0, int k0, const float* g, bf16* WT, int ldk, int drow0, LAS float* scr, int lane) {
;     ...
;     for (int i = 0; i < 16; ++i) { const int kk = 4 * i + kr; f32x4 v = *(const f32x4*)(W + (size_t)(k0 + kk) * ldn + col0 + n4); if (g) v = v * g[k0 + kk];
;         LAS float* d = scr + kk * 65 + n4; d[0] = v.x; d[1] = v.y; d[2] = v.z; d[3] = v.w; }
.Lofl_gdone:
	global_load_dwordx4 v[146:149], v232, s[2:3] nt
	v_add_u32_e32 v232, s38, v232
	global_load_dwordx4 v[150:153], v232, s[2:3] nt
	v_add_u32_e32 v232, s38, v232
	global_load_dwordx4 v[154:157], v232, s[2:3] nt
	v_add_u32_e32 v232, s38, v232
	global_load_dwordx4 v[158:161], v232, s[2:3] nt
	v_add_u32_e32 v232, s38, v232
	global_load_dwordx4 v[166:169], v232, s[2:3] nt
	v_add_u32_e32 v232, s38, v232
	global_load_dwordx4 v[170:173], v232, s[2:3] nt
	v_add_u32_e32 v232, s38, v232
	global_load_dwordx4 v[174:177], v232, s[2:3] nt
	v_add_u32_e32 v232, s38, v232
	global_load_dwordx4 v[178:181], v232, s[2:3] nt
	v_add_u32_e32 v232, s38, v232
	global_load_dwordx4 v[182:185], v232, s[2:3] nt
	v_add_u32_e32 v232, s38, v232
	global_load_dwordx4 v[186:189], v232, s[2:3] nt
	v_add_u32_e32 v232, s38, v232
	global_load_dwordx4 v[190:193], v232, s[2:3] nt
	v_add_u32_e32 v232, s38, v232
	global_load_dwordx4 v[108:111], v232, s[2:3] nt
	v_add_u32_e32 v232, s38, v232
	global_load_dwordx4 v[112:115], v232, s[2:3] nt
	v_add_u32_e32 v232, s38, v232
	global_load_dwordx4 v[116:119], v232, s[2:3] nt
	v_add_u32_e32 v232, s38, v232
	global_load_dwordx4 v[120:123], v232, s[2:3] nt
	v_add_u32_e32 v232, s38, v232
	global_load_dwordx4 v[124:127], v232, s[2:3] nt
	s_waitcnt vmcnt(15)
	v_mul_f32_e32 v146, v210, v146
	v_mul_f32_e32 v147, v210, v147
	v_mul_f32_e32 v148, v210, v148
	v_mul_f32_e32 v149, v210, v149
	ds_write2_b32 v242, v146, v147 offset1:1
	ds_write2_b32 v242, v148, v149 offset0:2 offset1:3
	v_add_u32_e32 v242, 0x410, v242
	s_waitcnt vmcnt(14)
	v_mul_f32_e32 v150, v211, v150
	v_mul_f32_e32 v151, v211, v151
	v_mul_f32_e32 v152, v211, v152
	v_mul_f32_e32 v153, v211, v153
	ds_write2_b32 v242, v150, v151 offset1:1
	ds_write2_b32 v242, v152, v153 offset0:2 offset1:3
	v_add_u32_e32 v242, 0x410, v242
	s_waitcnt vmcnt(13)
	v_mul_f32_e32 v154, v212, v154
	v_mul_f32_e32 v155, v212, v155
	v_mul_f32_e32 v156, v212, v156
	v_mul_f32_e32 v157, v212, v157
	ds_write2_b32 v242, v154, v155 offset1:1
	ds_write2_b32 v242, v156, v157 offset0:2 offset1:3
	v_add_u32_e32 v242, 0x410, v242
	s_waitcnt vmcnt(12)
	v_mul_f32_e32 v158, v213, v158
	v_mul_f32_e32 v159, v213, v159
	v_mul_f32_e32 v160, v213, v160
	v_mul_f32_e32 v161, v213, v161
	ds_write2_b32 v242, v158, v159 offset1:1
	ds_write2_b32 v242, v160, v161 offset0:2 offset1:3
	v_add_u32_e32 v242, 0x410, v242
	s_waitcnt vmcnt(11)
	v_mul_f32_e32 v166, v214, v166
	v_mul_f32_e32 v167, v214, v167
	v_mul_f32_e32 v168, v214, v168
	v_mul_f32_e32 v169, v214, v169
	ds_write2_b32 v242, v166, v167 offset1:1
	ds_write2_b32 v242, v168, v169 offset0:2 offset1:3
	v_add_u32_e32 v242, 0x410, v242
	s_waitcnt vmcnt(10)
	v_mul_f32_e32 v170, v215, v170
	v_mul_f32_e32 v171, v215, v171
	v_mul_f32_e32 v172, v215, v172
	v_mul_f32_e32 v173, v215, v173
	ds_write2_b32 v242, v170, v171 offset1:1
	ds_write2_b32 v242, v172, v173 offset0:2 offset1:3
	v_add_u32_e32 v242, 0x410, v242
	s_waitcnt vmcnt(9)
	v_mul_f32_e32 v174, v216, v174
	v_mul_f32_e32 v175, v216, v175
	v_mul_f32_e32 v176, v216, v176
	v_mul_f32_e32 v177, v216, v177
	ds_write2_b32 v242, v174, v175 offset1:1
	ds_write2_b32 v242, v176, v177 offset0:2 offset1:3
	v_add_u32_e32 v242, 0x410, v242
	s_waitcnt vmcnt(8)
	v_mul_f32_e32 v178, v217, v178
	v_mul_f32_e32 v179, v217, v179
	v_mul_f32_e32 v180, v217, v180
	v_mul_f32_e32 v181, v217, v181
	ds_write2_b32 v242, v178, v179 offset1:1
	ds_write2_b32 v242, v180, v181 offset0:2 offset1:3
	v_add_u32_e32 v242, 0x410, v242
	s_waitcnt vmcnt(7)
	v_mul_f32_e32 v182, v218, v182
	v_mul_f32_e32 v183, v218, v183
	v_mul_f32_e32 v184, v218, v184
	v_mul_f32_e32 v185, v218, v185
	ds_write2_b32 v242, v182, v183 offset1:1
	ds_write2_b32 v242, v184, v185 offset0:2 offset1:3
	v_add_u32_e32 v242, 0x410, v242
	s_waitcnt vmcnt(6)
	v_mul_f32_e32 v186, v219, v186
	v_mul_f32_e32 v187, v219, v187
	v_mul_f32_e32 v188, v219, v188
	v_mul_f32_e32 v189, v219, v189
	ds_write2_b32 v242, v186, v187 offset1:1
	ds_write2_b32 v242, v188, v189 offset0:2 offset1:3
	v_add_u32_e32 v242, 0x410, v242
	s_waitcnt vmcnt(5)
	v_mul_f32_e32 v190, v220, v190
	v_mul_f32_e32 v191, v220, v191
	v_mul_f32_e32 v192, v220, v192
	v_mul_f32_e32 v193, v220, v193
	ds_write2_b32 v242, v190, v191 offset1:1
	ds_write2_b32 v242, v192, v193 offset0:2 offset1:3
	v_add_u32_e32 v242, 0x410, v242
	s_waitcnt vmcnt(4)
	v_mul_f32_e32 v108, v221, v108
	v_mul_f32_e32 v109, v221, v109
	v_mul_f32_e32 v110, v221, v110
	v_mul_f32_e32 v111, v221, v111
	ds_write2_b32 v242, v108, v109 offset1:1
	ds_write2_b32 v242, v110, v111 offset0:2 offset1:3
	v_add_u32_e32 v242, 0x410, v242
	s_waitcnt vmcnt(3)
; #define LAS __attribute__((address_space(3)))
; __device__ __forceinline__ unsigned pk2(float lo, float hi) { return f2bf(lo) | (f2bf(hi) << 16); }
; #define LDS_WAIT() asm volatile("s_waitcnt lgkmcnt(0)" ::: "memory")
; __device__ __forceinline__ void tr_item(const float* W, int ldn, int col0, int k0, const float* g, bf16* WT, int ldk, int drow0, LAS float* scr, int lane) {
;     ...
;     LDS_WAIT(); asm volatile("" ::: "memory");
;     const int c = lane & 7;
; #pragma unroll
;     for (int j = 0; j < 8; ++j) { const int n = (lane >> 3) + 8 * j; const LAS float* s = scr + (8 * c) * 65 + n;
;         v4u o; o.x = pk2(s[0 * 65], s[1 * 65]); o.y = pk2(s[2 * 65], s[3 * 65]); o.z = pk2(s[4 * 65], s[5 * 65]); o.w = pk2(s[6 * 65], s[7 * 65]);
;         *(v4u*)(WT + (size_t)(drow0 + n) * ldk + k0 + 8 * c) = o; }
	v_mul_f32_e32 v112, v222, v112
	v_mul_f32_e32 v113, v222, v113
	v_mul_f32_e32 v114, v222, v114
	v_mul_f32_e32 v115, v222, v115
	ds_write2_b32 v242, v112, v113 offset1:1
	ds_write2_b32 v242, v114, v115 offset0:2 offset1:3
	v_add_u32_e32 v242, 0x410, v242
	s_waitcnt vmcnt(2)
	v_mul_f32_e32 v116, v223, v116
	v_mul_f32_e32 v117, v223, v117
	v_mul_f32_e32 v118, v223, v118
	v_mul_f32_e32 v119, v223, v119
	ds_write2_b32 v242, v116, v117 offset1:1
	ds_write2_b32 v242, v118, v119 offset0:2 offset1:3
	v_add_u32_e32 v242, 0x410, v242
	s_waitcnt vmcnt(1)
	v_mul_f32_e32 v120, v230, v120
	v_mul_f32_e32 v121, v230, v121
	v_mul_f32_e32 v122, v230, v122
	v_mul_f32_e32 v123, v230, v123
	ds_write2_b32 v242, v120, v121 offset1:1
	ds_write2_b32 v242, v122, v123 offset0:2 offset1:3
	v_add_u32_e32 v242, 0x410, v242
	s_waitcnt vmcnt(0)
	v_mul_f32_e32 v124, v231, v124
	v_mul_f32_e32 v125, v231, v125
	v_mul_f32_e32 v126, v231, v126
	v_mul_f32_e32 v127, v231, v127
	ds_write2_b32 v242, v124, v125 offset1:1
	ds_write2_b32 v242, v126, v127 offset0:2 offset1:3
	s_waitcnt lgkmcnt(0)
	ds_read2_b32 v[146:147], v48 offset0:0 offset1:65
	ds_read2_b32 v[148:149], v48 offset0:130 offset1:195
	ds_read2_b32 v[150:151], v243 offset0:4 offset1:69
	ds_read2_b32 v[152:153], v243 offset0:134 offset1:199
	ds_read2_b32 v[154:155], v48 offset0:8 offset1:73
	ds_read2_b32 v[156:157], v48 offset0:138 offset1:203
	ds_read2_b32 v[158:159], v243 offset0:12 offset1:77
	ds_read2_b32 v[160:161], v243 offset0:142 offset1:207
	ds_read2_b32 v[166:167], v48 offset0:16 offset1:81
	ds_read2_b32 v[168:169], v48 offset0:146 offset1:211
	ds_read2_b32 v[170:171], v243 offset0:20 offset1:85
	ds_read2_b32 v[172:173], v243 offset0:150 offset1:215
	s_waitcnt lgkmcnt(8)
	v_cvt_pk_bf16_f32 v146, v146, v147
	v_cvt_pk_bf16_f32 v147, v148, v149
	v_cvt_pk_bf16_f32 v148, v150, v151
	v_cvt_pk_bf16_f32 v149, v152, v153
	global_store_dwordx4 v244, v[146:149], s[24:25]
	ds_read2_b32 v[174:175], v48 offset0:24 offset1:89
	ds_read2_b32 v[176:177], v48 offset0:154 offset1:219
	ds_read2_b32 v[178:179], v243 offset0:28 offset1:93
	ds_read2_b32 v[180:181], v243 offset0:158 offset1:223
	s_waitcnt lgkmcnt(8)
	v_cvt_pk_bf16_f32 v154, v154, v155
	v_cvt_pk_bf16_f32 v155, v156, v157
	v_cvt_pk_bf16_f32 v156, v158, v159
	v_cvt_pk_bf16_f32 v157, v160, v161
	global_store_dwordx4 v245, v[154:157], s[24:25]
	ds_read2_b32 v[182:183], v48 offset0:32 offset1:97
	ds_read2_b32 v[184:185], v48 offset0:162 offset1:227
	ds_read2_b32 v[186:187], v243 offset0:36 offset1:101
	ds_read2_b32 v[188:189], v243 offset0:166 offset1:231
	s_waitcnt lgkmcnt(8)
	v_cvt_pk_bf16_f32 v166, v166, v167
	v_cvt_pk_bf16_f32 v167, v168, v169
	v_cvt_pk_bf16_f32 v168, v170, v171
	v_cvt_pk_bf16_f32 v169, v172, v173
	global_store_dwordx4 v246, v[166:169], s[24:25]
	ds_read2_b32 v[108:109], v48 offset0:40 offset1:105
	ds_read2_b32 v[110:111], v48 offset0:170 offset1:235
	ds_read2_b32 v[112:113], v243 offset0:44 offset1:109
	ds_read2_b32 v[114:115], v243 offset0:174 offset1:239
	s_waitcnt lgkmcnt(8)
	v_cvt_pk_bf16_f32 v174, v174, v175
	v_cvt_pk_bf16_f32 v175, v176, v177
	v_cvt_pk_bf16_f32 v176, v178, v179
	v_cvt_pk_bf16_f32 v177, v180, v181
	global_store_dwordx4 v247, v[174:177], s[24:25]
	ds_read2_b32 v[116:117], v48 offset0:48 offset1:113
	ds_read2_b32 v[118:119], v48 offset0:178 offset1:243
	ds_read2_b32 v[120:121], v243 offset0:52 offset1:117
	ds_read2_b32 v[122:123], v243 offset0:182 offset1:247
	s_waitcnt lgkmcnt(8)
	v_cvt_pk_bf16_f32 v182, v182, v183
	v_cvt_pk_bf16_f32 v183, v184, v185
	v_cvt_pk_bf16_f32 v184, v186, v187
	v_cvt_pk_bf16_f32 v185, v188, v189
	global_store_dwordx4 v248, v[182:185], s[24:25]
	ds_read2_b32 v[124:125], v48 offset0:56 offset1:121
	ds_read2_b32 v[126:127], v48 offset0:186 offset1:251
	ds_read2_b32 v[128:129], v243 offset0:60 offset1:125
	ds_read2_b32 v[130:131], v243 offset0:190 offset1:255
	s_waitcnt lgkmcnt(8)
	v_cvt_pk_bf16_f32 v108, v108, v109
	v_cvt_pk_bf16_f32 v109, v110, v111
	v_cvt_pk_bf16_f32 v110, v112, v113
	v_cvt_pk_bf16_f32 v111, v114, v115
	global_store_dwordx4 v249, v[108:111], s[24:25]
	s_waitcnt lgkmcnt(4)
	v_cvt_pk_bf16_f32 v116, v116, v117
	v_cvt_pk_bf16_f32 v117, v118, v119
	v_cvt_pk_bf16_f32 v118, v120, v121
	v_cvt_pk_bf16_f32 v119, v122, v123
	global_store_dwordx4 v250, v[116:119], s[24:25]
	s_waitcnt lgkmcnt(0)
	v_cvt_pk_bf16_f32 v124, v124, v125
	v_cvt_pk_bf16_f32 v125, v126, v127
	v_cvt_pk_bf16_f32 v126, v128, v129
	v_cvt_pk_bf16_f32 v127, v130, v131
	global_store_dwordx4 v251, v[124:127], s[24:25]
	s_addk_i32 s10, 0x400
	s_cmpk_lt_u32 s10, 0x1200
	s_cbranch_scc1 .Lofl_item
